# SwiGLU epilogues (P1,P9) re-emitted: packed f32 mul/add for the silu*u chains, transcendentals batched per row group, no hazard nops; same arithmetic; on top of v17
# speedup vs baseline: 1.0052x; 1.0010x over previous
; __device__ __forceinline__ unsigned cvt_pk_bf16(float lo, float hi) { unsigned r; asm volatile("v_cvt_pk_bf16_f32 %0, %1, %2" : "=v"(r) : "v"(lo), "v"(hi)); return r; }
; __device__ __forceinline__ float silu_f(float x) { return x * __builtin_amdgcn_rcpf(1.0f + __builtin_amdgcn_exp2f(-1.4426950408889634f * x)); }
;     __device__ __forceinline__ void operator()(const f32x4 (&acc)[2][2][4][2], const Unit& u, int wr, int wc, int fr, int fq) const {
;         const int row0 = u.pm * BM + wr * 64 + fr, col0 = u.pn * HALF + wc * 32 + 8 * fq;
; #pragma unroll
;         for (int ai = 0; ai < 2; ++ai)
; #pragma unroll
;             for (int m = 0; m < 4; ++m) { bf16_t* rowp = H + (size_t)(row0 + ai * HALF + m * 16) * ldc + col0;
;                 const f32x4 g0 = acc[ai][0][m][0], g1 = acc[ai][0][m][1], u0 = acc[ai][1][m][0], u1 = acc[ai][1][m][1];
;                 u32x4 w;
;                 w.x = cvt_pk_bf16(silu_f(g0[0]) * u0[0], silu_f(g0[1]) * u0[1]); w.y = cvt_pk_bf16(silu_f(g0[2]) * u0[2], silu_f(g0[3]) * u0[3]);
;                 w.z = cvt_pk_bf16(silu_f(g1[0]) * u1[0], silu_f(g1[1]) * u1[1]); w.w = cvt_pk_bf16(silu_f(g1[2]) * u1[2], silu_f(g1[3]) * u1[3]);
;                 *(u32x4*)rowp = w; }
.LBB0_105:
	v_lshl_or_b32 v148, s43, 7, v151
	v_lshl_add_u32 v155, s24, 8, v1
	v_ashrrev_i32_e32 v149, 31, v148
	v_mov_b64_e32 v[146:147], s[58:59]
	v_lshlrev_b64 v[148:149], 1, v[148:149]
	s_mov_b32 s98, 0xbfb8aa3b
	v_mad_i64_i32 v[188:189], s[2:3], v155, s42, v[146:147]
	v_lshl_add_u64 v[188:189], v[188:189], 0, v[148:149]
	v_pk_mul_f32 v[176:177], v[126:127], s[98:99] op_sel_hi:[1,0]
	v_pk_mul_f32 v[178:179], v[128:129], s[98:99] op_sel_hi:[1,0]
	v_pk_mul_f32 v[180:181], v[118:119], s[98:99] op_sel_hi:[1,0]
	v_pk_mul_f32 v[182:183], v[120:121], s[98:99] op_sel_hi:[1,0]
	v_exp_f32_e32 v176, v176
	v_exp_f32_e32 v177, v177
	v_exp_f32_e32 v178, v178
	v_exp_f32_e32 v179, v179
	v_exp_f32_e32 v180, v180
	v_exp_f32_e32 v181, v181
	v_exp_f32_e32 v182, v182
	v_exp_f32_e32 v183, v183
	v_pk_add_f32 v[176:177], v[176:177], 1.0 op_sel_hi:[1,0]
	v_pk_add_f32 v[178:179], v[178:179], 1.0 op_sel_hi:[1,0]
	v_pk_add_f32 v[180:181], v[180:181], 1.0 op_sel_hi:[1,0]
	v_pk_add_f32 v[182:183], v[182:183], 1.0 op_sel_hi:[1,0]
	v_rcp_f32_e32 v176, v176
	v_rcp_f32_e32 v177, v177
	v_rcp_f32_e32 v178, v178
	v_rcp_f32_e32 v179, v179
	v_rcp_f32_e32 v180, v180
	v_rcp_f32_e32 v181, v181
	v_rcp_f32_e32 v182, v182
	v_rcp_f32_e32 v183, v183
	v_pk_mul_f32 v[176:177], v[126:127], v[176:177]
	v_pk_mul_f32 v[178:179], v[128:129], v[178:179]
	v_pk_mul_f32 v[180:181], v[118:119], v[180:181]
	v_pk_mul_f32 v[182:183], v[120:121], v[182:183]
	v_pk_mul_f32 v[176:177], v[176:177], v[122:123]
	v_pk_mul_f32 v[178:179], v[178:179], v[124:125]
	v_pk_mul_f32 v[180:181], v[180:181], v[114:115]
	v_pk_mul_f32 v[182:183], v[182:183], v[116:117]
	v_cvt_pk_bf16_f32 v184, v176, v177
	v_cvt_pk_bf16_f32 v185, v178, v179
	v_cvt_pk_bf16_f32 v186, v180, v181
	v_cvt_pk_bf16_f32 v187, v182, v183
	global_store_dwordx4 v[188:189], v[184:187], off
	v_or_b32_e32 v212, 16, v155
	v_mad_i64_i32 v[210:211], s[2:3], v212, s42, v[146:147]
	v_lshl_add_u64 v[210:211], v[210:211], 0, v[148:149]
	v_pk_mul_f32 v[198:199], v[110:111], s[98:99] op_sel_hi:[1,0]
	v_pk_mul_f32 v[200:201], v[112:113], s[98:99] op_sel_hi:[1,0]
	v_pk_mul_f32 v[202:203], v[102:103], s[98:99] op_sel_hi:[1,0]
	v_pk_mul_f32 v[204:205], v[104:105], s[98:99] op_sel_hi:[1,0]
	v_exp_f32_e32 v198, v198
	v_exp_f32_e32 v199, v199
	v_exp_f32_e32 v200, v200
	v_exp_f32_e32 v201, v201
	v_exp_f32_e32 v202, v202
	v_exp_f32_e32 v203, v203
	v_exp_f32_e32 v204, v204
	v_exp_f32_e32 v205, v205
	v_pk_add_f32 v[198:199], v[198:199], 1.0 op_sel_hi:[1,0]
	v_pk_add_f32 v[200:201], v[200:201], 1.0 op_sel_hi:[1,0]
	v_pk_add_f32 v[202:203], v[202:203], 1.0 op_sel_hi:[1,0]
	v_pk_add_f32 v[204:205], v[204:205], 1.0 op_sel_hi:[1,0]
	v_rcp_f32_e32 v198, v198
	v_rcp_f32_e32 v199, v199
	v_rcp_f32_e32 v200, v200
	v_rcp_f32_e32 v201, v201
	v_rcp_f32_e32 v202, v202
	v_rcp_f32_e32 v203, v203
	v_rcp_f32_e32 v204, v204
	v_rcp_f32_e32 v205, v205
	v_pk_mul_f32 v[198:199], v[110:111], v[198:199]
	v_pk_mul_f32 v[200:201], v[112:113], v[200:201]
	v_pk_mul_f32 v[202:203], v[102:103], v[202:203]
	v_pk_mul_f32 v[204:205], v[104:105], v[204:205]
	v_pk_mul_f32 v[198:199], v[198:199], v[106:107]
	v_pk_mul_f32 v[200:201], v[200:201], v[108:109]
	v_pk_mul_f32 v[202:203], v[202:203], v[98:99]
	v_pk_mul_f32 v[204:205], v[204:205], v[100:101]
	v_cvt_pk_bf16_f32 v206, v198, v199
	v_cvt_pk_bf16_f32 v207, v200, v201
	v_cvt_pk_bf16_f32 v208, v202, v203
	v_cvt_pk_bf16_f32 v209, v204, v205
	global_store_dwordx4 v[210:211], v[206:209], off
	v_or_b32_e32 v190, 32, v155
	v_mad_i64_i32 v[188:189], s[2:3], v190, s42, v[146:147]
	v_lshl_add_u64 v[188:189], v[188:189], 0, v[148:149]
	v_pk_mul_f32 v[176:177], v[94:95], s[98:99] op_sel_hi:[1,0]
	v_pk_mul_f32 v[178:179], v[96:97], s[98:99] op_sel_hi:[1,0]
	v_pk_mul_f32 v[180:181], v[86:87], s[98:99] op_sel_hi:[1,0]
	v_pk_mul_f32 v[182:183], v[88:89], s[98:99] op_sel_hi:[1,0]
	v_exp_f32_e32 v176, v176
	v_exp_f32_e32 v177, v177
	v_exp_f32_e32 v178, v178
	v_exp_f32_e32 v179, v179
	v_exp_f32_e32 v180, v180
	v_exp_f32_e32 v181, v181
	v_exp_f32_e32 v182, v182
	v_exp_f32_e32 v183, v183
	v_pk_add_f32 v[176:177], v[176:177], 1.0 op_sel_hi:[1,0]
	v_pk_add_f32 v[178:179], v[178:179], 1.0 op_sel_hi:[1,0]
	v_pk_add_f32 v[180:181], v[180:181], 1.0 op_sel_hi:[1,0]
	v_pk_add_f32 v[182:183], v[182:183], 1.0 op_sel_hi:[1,0]
	v_rcp_f32_e32 v176, v176
	v_rcp_f32_e32 v177, v177
	v_rcp_f32_e32 v178, v178
	v_rcp_f32_e32 v179, v179
	v_rcp_f32_e32 v180, v180
	v_rcp_f32_e32 v181, v181
	v_rcp_f32_e32 v182, v182
	v_rcp_f32_e32 v183, v183
	v_pk_mul_f32 v[176:177], v[94:95], v[176:177]
	v_pk_mul_f32 v[178:179], v[96:97], v[178:179]
	v_pk_mul_f32 v[180:181], v[86:87], v[180:181]
	v_pk_mul_f32 v[182:183], v[88:89], v[182:183]
	v_pk_mul_f32 v[176:177], v[176:177], v[90:91]
	v_pk_mul_f32 v[178:179], v[178:179], v[92:93]
	v_pk_mul_f32 v[180:181], v[180:181], v[82:83]
	v_pk_mul_f32 v[182:183], v[182:183], v[84:85]
	v_cvt_pk_bf16_f32 v184, v176, v177
	v_cvt_pk_bf16_f32 v185, v178, v179
	v_cvt_pk_bf16_f32 v186, v180, v181
	v_cvt_pk_bf16_f32 v187, v182, v183
	global_store_dwordx4 v[188:189], v[184:187], off
	v_or_b32_e32 v212, 48, v155
	v_mad_i64_i32 v[210:211], s[2:3], v212, s42, v[146:147]
	v_lshl_add_u64 v[210:211], v[210:211], 0, v[148:149]
	v_pk_mul_f32 v[198:199], v[78:79], s[98:99] op_sel_hi:[1,0]
	v_pk_mul_f32 v[200:201], v[80:81], s[98:99] op_sel_hi:[1,0]
	v_pk_mul_f32 v[202:203], v[70:71], s[98:99] op_sel_hi:[1,0]
	v_pk_mul_f32 v[204:205], v[72:73], s[98:99] op_sel_hi:[1,0]
	v_exp_f32_e32 v198, v198
	v_exp_f32_e32 v199, v199
	v_exp_f32_e32 v200, v200
	v_exp_f32_e32 v201, v201
	v_exp_f32_e32 v202, v202
	v_exp_f32_e32 v203, v203
	v_exp_f32_e32 v204, v204
	v_exp_f32_e32 v205, v205
; __device__ __forceinline__ unsigned cvt_pk_bf16(float lo, float hi) { unsigned r; asm volatile("v_cvt_pk_bf16_f32 %0, %1, %2" : "=v"(r) : "v"(lo), "v"(hi)); return r; }
; __device__ __forceinline__ float silu_f(float x) { return x * __builtin_amdgcn_rcpf(1.0f + __builtin_amdgcn_exp2f(-1.4426950408889634f * x)); }
;     __device__ __forceinline__ void operator()(const f32x4 (&acc)[2][2][4][2], const Unit& u, int wr, int wc, int fr, int fq) const {
;         const int row0 = u.pm * BM + wr * 64 + fr, col0 = u.pn * HALF + wc * 32 + 8 * fq;
; #pragma unroll
;         for (int ai = 0; ai < 2; ++ai)
; #pragma unroll
;             for (int m = 0; m < 4; ++m) { bf16_t* rowp = H + (size_t)(row0 + ai * HALF + m * 16) * ldc + col0;
;                 const f32x4 g0 = acc[ai][0][m][0], g1 = acc[ai][0][m][1], u0 = acc[ai][1][m][0], u1 = acc[ai][1][m][1];
;                 u32x4 w;
;                 w.x = cvt_pk_bf16(silu_f(g0[0]) * u0[0], silu_f(g0[1]) * u0[1]); w.y = cvt_pk_bf16(silu_f(g0[2]) * u0[2], silu_f(g0[3]) * u0[3]);
;                 w.z = cvt_pk_bf16(silu_f(g1[0]) * u1[0], silu_f(g1[1]) * u1[1]); w.w = cvt_pk_bf16(silu_f(g1[2]) * u1[2], silu_f(g1[3]) * u1[3]);
;                 *(u32x4*)rowp = w; }
	v_pk_add_f32 v[198:199], v[198:199], 1.0 op_sel_hi:[1,0]
	v_pk_add_f32 v[200:201], v[200:201], 1.0 op_sel_hi:[1,0]
	v_pk_add_f32 v[202:203], v[202:203], 1.0 op_sel_hi:[1,0]
	v_pk_add_f32 v[204:205], v[204:205], 1.0 op_sel_hi:[1,0]
	v_rcp_f32_e32 v198, v198
	v_rcp_f32_e32 v199, v199
	v_rcp_f32_e32 v200, v200
	v_rcp_f32_e32 v201, v201
	v_rcp_f32_e32 v202, v202
	v_rcp_f32_e32 v203, v203
	v_rcp_f32_e32 v204, v204
	v_rcp_f32_e32 v205, v205
	v_pk_mul_f32 v[198:199], v[78:79], v[198:199]
	v_pk_mul_f32 v[200:201], v[80:81], v[200:201]
	v_pk_mul_f32 v[202:203], v[70:71], v[202:203]
	v_pk_mul_f32 v[204:205], v[72:73], v[204:205]
	v_pk_mul_f32 v[198:199], v[198:199], v[74:75]
	v_pk_mul_f32 v[200:201], v[200:201], v[76:77]
	v_pk_mul_f32 v[202:203], v[202:203], v[66:67]
	v_pk_mul_f32 v[204:205], v[204:205], v[68:69]
	v_cvt_pk_bf16_f32 v206, v198, v199
	v_cvt_pk_bf16_f32 v207, v200, v201
	v_cvt_pk_bf16_f32 v208, v202, v203
	v_cvt_pk_bf16_f32 v209, v204, v205
	global_store_dwordx4 v[210:211], v[206:209], off
	v_add_u32_e32 v190, 0x80, v155
	v_mad_i64_i32 v[188:189], s[2:3], v190, s42, v[146:147]
	v_lshl_add_u64 v[188:189], v[188:189], 0, v[148:149]
	v_pk_mul_f32 v[176:177], v[62:63], s[98:99] op_sel_hi:[1,0]
	v_pk_mul_f32 v[178:179], v[64:65], s[98:99] op_sel_hi:[1,0]
	v_pk_mul_f32 v[180:181], v[54:55], s[98:99] op_sel_hi:[1,0]
	v_pk_mul_f32 v[182:183], v[56:57], s[98:99] op_sel_hi:[1,0]
	v_exp_f32_e32 v176, v176
	v_exp_f32_e32 v177, v177
	v_exp_f32_e32 v178, v178
	v_exp_f32_e32 v179, v179
	v_exp_f32_e32 v180, v180
	v_exp_f32_e32 v181, v181
	v_exp_f32_e32 v182, v182
	v_exp_f32_e32 v183, v183
	v_pk_add_f32 v[176:177], v[176:177], 1.0 op_sel_hi:[1,0]
	v_pk_add_f32 v[178:179], v[178:179], 1.0 op_sel_hi:[1,0]
	v_pk_add_f32 v[180:181], v[180:181], 1.0 op_sel_hi:[1,0]
	v_pk_add_f32 v[182:183], v[182:183], 1.0 op_sel_hi:[1,0]
	v_rcp_f32_e32 v176, v176
	v_rcp_f32_e32 v177, v177
	v_rcp_f32_e32 v178, v178
	v_rcp_f32_e32 v179, v179
	v_rcp_f32_e32 v180, v180
	v_rcp_f32_e32 v181, v181
	v_rcp_f32_e32 v182, v182
	v_rcp_f32_e32 v183, v183
	v_pk_mul_f32 v[176:177], v[62:63], v[176:177]
	v_pk_mul_f32 v[178:179], v[64:65], v[178:179]
	v_pk_mul_f32 v[180:181], v[54:55], v[180:181]
	v_pk_mul_f32 v[182:183], v[56:57], v[182:183]
	v_pk_mul_f32 v[176:177], v[176:177], v[58:59]
	v_pk_mul_f32 v[178:179], v[178:179], v[60:61]
	v_pk_mul_f32 v[180:181], v[180:181], v[50:51]
	v_pk_mul_f32 v[182:183], v[182:183], v[52:53]
	v_cvt_pk_bf16_f32 v184, v176, v177
	v_cvt_pk_bf16_f32 v185, v178, v179
	v_cvt_pk_bf16_f32 v186, v180, v181
	v_cvt_pk_bf16_f32 v187, v182, v183
	global_store_dwordx4 v[188:189], v[184:187], off
	v_add_u32_e32 v212, 0x90, v155
	v_mad_i64_i32 v[210:211], s[2:3], v212, s42, v[146:147]
	v_lshl_add_u64 v[210:211], v[210:211], 0, v[148:149]
	v_pk_mul_f32 v[198:199], v[46:47], s[98:99] op_sel_hi:[1,0]
	v_pk_mul_f32 v[200:201], v[48:49], s[98:99] op_sel_hi:[1,0]
	v_pk_mul_f32 v[202:203], v[38:39], s[98:99] op_sel_hi:[1,0]
	v_pk_mul_f32 v[204:205], v[40:41], s[98:99] op_sel_hi:[1,0]
	v_exp_f32_e32 v198, v198
	v_exp_f32_e32 v199, v199
	v_exp_f32_e32 v200, v200
	v_exp_f32_e32 v201, v201
	v_exp_f32_e32 v202, v202
	v_exp_f32_e32 v203, v203
	v_exp_f32_e32 v204, v204
	v_exp_f32_e32 v205, v205
	v_pk_add_f32 v[198:199], v[198:199], 1.0 op_sel_hi:[1,0]
	v_pk_add_f32 v[200:201], v[200:201], 1.0 op_sel_hi:[1,0]
	v_pk_add_f32 v[202:203], v[202:203], 1.0 op_sel_hi:[1,0]
	v_pk_add_f32 v[204:205], v[204:205], 1.0 op_sel_hi:[1,0]
	v_rcp_f32_e32 v198, v198
	v_rcp_f32_e32 v199, v199
	v_rcp_f32_e32 v200, v200
	v_rcp_f32_e32 v201, v201
	v_rcp_f32_e32 v202, v202
	v_rcp_f32_e32 v203, v203
	v_rcp_f32_e32 v204, v204
	v_rcp_f32_e32 v205, v205
	v_pk_mul_f32 v[198:199], v[46:47], v[198:199]
	v_pk_mul_f32 v[200:201], v[48:49], v[200:201]
	v_pk_mul_f32 v[202:203], v[38:39], v[202:203]
; __device__ __forceinline__ unsigned cvt_pk_bf16(float lo, float hi) { unsigned r; asm volatile("v_cvt_pk_bf16_f32 %0, %1, %2" : "=v"(r) : "v"(lo), "v"(hi)); return r; }
; __device__ __forceinline__ float silu_f(float x) { return x * __builtin_amdgcn_rcpf(1.0f + __builtin_amdgcn_exp2f(-1.4426950408889634f * x)); }
;     __device__ __forceinline__ void operator()(const f32x4 (&acc)[2][2][4][2], const Unit& u, int wr, int wc, int fr, int fq) const {
;         const int row0 = u.pm * BM + wr * 64 + fr, col0 = u.pn * HALF + wc * 32 + 8 * fq;
; #pragma unroll
;         for (int ai = 0; ai < 2; ++ai)
; #pragma unroll
;             for (int m = 0; m < 4; ++m) { bf16_t* rowp = H + (size_t)(row0 + ai * HALF + m * 16) * ldc + col0;
;                 const f32x4 g0 = acc[ai][0][m][0], g1 = acc[ai][0][m][1], u0 = acc[ai][1][m][0], u1 = acc[ai][1][m][1];
;                 u32x4 w;
;                 w.x = cvt_pk_bf16(silu_f(g0[0]) * u0[0], silu_f(g0[1]) * u0[1]); w.y = cvt_pk_bf16(silu_f(g0[2]) * u0[2], silu_f(g0[3]) * u0[3]);
;                 w.z = cvt_pk_bf16(silu_f(g1[0]) * u1[0], silu_f(g1[1]) * u1[1]); w.w = cvt_pk_bf16(silu_f(g1[2]) * u1[2], silu_f(g1[3]) * u1[3]);
;                 *(u32x4*)rowp = w; }
; template <class Epi, class Sched, bool ALIGN_EPI = false, bool SP2 = false>
; __device__ __forceinline__ void gemm_phase(PG8_LAS unsigned char* lds, const Gemm g, const Sched& S, const Epi& E) {
;     ...
;         if constexpr (!Epi::AFTER_DRAIN) { E(acc, cur, wr, wc, fr, fq); S.done(cur); }
;         if (!has_next) break;
	v_pk_mul_f32 v[204:205], v[40:41], v[204:205]
	v_pk_mul_f32 v[198:199], v[198:199], v[42:43]
	v_pk_mul_f32 v[200:201], v[200:201], v[44:45]
	v_pk_mul_f32 v[202:203], v[202:203], v[34:35]
	v_pk_mul_f32 v[204:205], v[204:205], v[36:37]
	v_cvt_pk_bf16_f32 v206, v198, v199
	v_cvt_pk_bf16_f32 v207, v200, v201
	v_cvt_pk_bf16_f32 v208, v202, v203
	v_cvt_pk_bf16_f32 v209, v204, v205
	global_store_dwordx4 v[210:211], v[206:209], off
	v_add_u32_e32 v190, 0xa0, v155
	v_mad_i64_i32 v[188:189], s[2:3], v190, s42, v[146:147]
	v_lshl_add_u64 v[188:189], v[188:189], 0, v[148:149]
	v_pk_mul_f32 v[176:177], v[30:31], s[98:99] op_sel_hi:[1,0]
	v_pk_mul_f32 v[178:179], v[32:33], s[98:99] op_sel_hi:[1,0]
	v_pk_mul_f32 v[180:181], v[22:23], s[98:99] op_sel_hi:[1,0]
	v_pk_mul_f32 v[182:183], v[24:25], s[98:99] op_sel_hi:[1,0]
	v_exp_f32_e32 v176, v176
	v_exp_f32_e32 v177, v177
	v_exp_f32_e32 v178, v178
	v_exp_f32_e32 v179, v179
	v_exp_f32_e32 v180, v180
	v_exp_f32_e32 v181, v181
	v_exp_f32_e32 v182, v182
	v_exp_f32_e32 v183, v183
	v_pk_add_f32 v[176:177], v[176:177], 1.0 op_sel_hi:[1,0]
	v_pk_add_f32 v[178:179], v[178:179], 1.0 op_sel_hi:[1,0]
	v_pk_add_f32 v[180:181], v[180:181], 1.0 op_sel_hi:[1,0]
	v_pk_add_f32 v[182:183], v[182:183], 1.0 op_sel_hi:[1,0]
	v_rcp_f32_e32 v176, v176
	v_rcp_f32_e32 v177, v177
	v_rcp_f32_e32 v178, v178
	v_rcp_f32_e32 v179, v179
	v_rcp_f32_e32 v180, v180
	v_rcp_f32_e32 v181, v181
	v_rcp_f32_e32 v182, v182
	v_rcp_f32_e32 v183, v183
	v_pk_mul_f32 v[176:177], v[30:31], v[176:177]
	v_pk_mul_f32 v[178:179], v[32:33], v[178:179]
	v_pk_mul_f32 v[180:181], v[22:23], v[180:181]
	v_pk_mul_f32 v[182:183], v[24:25], v[182:183]
	v_pk_mul_f32 v[176:177], v[176:177], v[26:27]
	v_pk_mul_f32 v[178:179], v[178:179], v[28:29]
	v_pk_mul_f32 v[180:181], v[180:181], v[18:19]
	v_pk_mul_f32 v[182:183], v[182:183], v[20:21]
	v_cvt_pk_bf16_f32 v184, v176, v177
	v_cvt_pk_bf16_f32 v185, v178, v179
	v_cvt_pk_bf16_f32 v186, v180, v181
	v_cvt_pk_bf16_f32 v187, v182, v183
	global_store_dwordx4 v[188:189], v[184:187], off
	v_add_u32_e32 v212, 0xb0, v155
	v_mad_i64_i32 v[210:211], s[2:3], v212, s42, v[146:147]
	v_lshl_add_u64 v[210:211], v[210:211], 0, v[148:149]
	v_pk_mul_f32 v[198:199], v[14:15], s[98:99] op_sel_hi:[1,0]
	v_pk_mul_f32 v[200:201], v[16:17], s[98:99] op_sel_hi:[1,0]
	v_pk_mul_f32 v[202:203], v[6:7], s[98:99] op_sel_hi:[1,0]
	v_pk_mul_f32 v[204:205], v[8:9], s[98:99] op_sel_hi:[1,0]
	v_exp_f32_e32 v198, v198
	v_exp_f32_e32 v199, v199
	v_exp_f32_e32 v200, v200
	v_exp_f32_e32 v201, v201
	v_exp_f32_e32 v202, v202
	v_exp_f32_e32 v203, v203
	v_exp_f32_e32 v204, v204
	v_exp_f32_e32 v205, v205
	v_pk_add_f32 v[198:199], v[198:199], 1.0 op_sel_hi:[1,0]
	v_pk_add_f32 v[200:201], v[200:201], 1.0 op_sel_hi:[1,0]
	v_pk_add_f32 v[202:203], v[202:203], 1.0 op_sel_hi:[1,0]
	v_pk_add_f32 v[204:205], v[204:205], 1.0 op_sel_hi:[1,0]
	v_rcp_f32_e32 v198, v198
	v_rcp_f32_e32 v199, v199
	v_rcp_f32_e32 v200, v200
	v_rcp_f32_e32 v201, v201
	v_rcp_f32_e32 v202, v202
	v_rcp_f32_e32 v203, v203
	v_rcp_f32_e32 v204, v204
	v_rcp_f32_e32 v205, v205
	v_pk_mul_f32 v[198:199], v[14:15], v[198:199]
	v_pk_mul_f32 v[200:201], v[16:17], v[200:201]
	v_pk_mul_f32 v[202:203], v[6:7], v[202:203]
	v_pk_mul_f32 v[204:205], v[8:9], v[204:205]
	v_pk_mul_f32 v[198:199], v[198:199], v[10:11]
	v_pk_mul_f32 v[200:201], v[200:201], v[12:13]
	v_pk_mul_f32 v[202:203], v[202:203], v[2:3]
	v_pk_mul_f32 v[204:205], v[204:205], v[4:5]
	v_cvt_pk_bf16_f32 v206, v198, v199
	v_cvt_pk_bf16_f32 v207, v200, v201
	v_cvt_pk_bf16_f32 v208, v202, v203
	v_cvt_pk_bf16_f32 v209, v204, v205
	global_store_dwordx4 v[210:211], v[206:209], off
	s_andn2_b64 vcc, exec, s[0:1]
	s_mov_b64 s[2:3], -1
	s_cbranch_vccnz .LBB0_94
	s_andn2_b64 vcc, exec, s[4:5]
	s_cbranch_vccnz .LBB0_93
	s_barrier
	s_branch .LBB0_93

; __device__ __forceinline__ unsigned cvt_pk_bf16(float lo, float hi) { unsigned r; asm volatile("v_cvt_pk_bf16_f32 %0, %1, %2" : "=v"(r) : "v"(lo), "v"(hi)); return r; }
; __device__ __forceinline__ float silu_f(float x) { return x * __builtin_amdgcn_rcpf(1.0f + __builtin_amdgcn_exp2f(-1.4426950408889634f * x)); }
;     __device__ __forceinline__ void operator()(const f32x4 (&acc)[2][2][4][2], const Unit& u, int wr, int wc, int fr, int fq) const {
;         const int row0 = u.pm * BM + wr * 64 + fr, col0 = u.pn * HALF + wc * 32 + 8 * fq;
; #pragma unroll
;         for (int ai = 0; ai < 2; ++ai)
; #pragma unroll
;             for (int m = 0; m < 4; ++m) { bf16_t* rowp = H + (size_t)(row0 + ai * HALF + m * 16) * ldc + col0;
;                 const f32x4 g0 = acc[ai][0][m][0], g1 = acc[ai][0][m][1], u0 = acc[ai][1][m][0], u1 = acc[ai][1][m][1];
;                 u32x4 w;
;                 w.x = cvt_pk_bf16(silu_f(g0[0]) * u0[0], silu_f(g0[1]) * u0[1]); w.y = cvt_pk_bf16(silu_f(g0[2]) * u0[2], silu_f(g0[3]) * u0[3]);
;                 w.z = cvt_pk_bf16(silu_f(g1[0]) * u1[0], silu_f(g1[1]) * u1[1]); w.w = cvt_pk_bf16(silu_f(g1[2]) * u1[2], silu_f(g1[3]) * u1[3]);
;                 *(u32x4*)rowp = w; }
.LBB0_1631:
	v_lshl_or_b32 v148, s45, 7, v152
	v_lshl_add_u32 v156, s30, 8, v150
	v_ashrrev_i32_e32 v149, 31, v148
	v_mov_b64_e32 v[146:147], s[68:69]
	v_lshlrev_b64 v[148:149], 1, v[148:149]
	s_mov_b32 s98, 0xbfb8aa3b
	v_mad_i64_i32 v[188:189], s[2:3], v156, s44, v[146:147]
	v_lshl_add_u64 v[188:189], v[188:189], 0, v[148:149]
	v_pk_mul_f32 v[176:177], v[126:127], s[98:99] op_sel_hi:[1,0]
	v_pk_mul_f32 v[178:179], v[128:129], s[98:99] op_sel_hi:[1,0]
	v_pk_mul_f32 v[180:181], v[122:123], s[98:99] op_sel_hi:[1,0]
	v_pk_mul_f32 v[182:183], v[124:125], s[98:99] op_sel_hi:[1,0]
	v_exp_f32_e32 v176, v176
	v_exp_f32_e32 v177, v177
	v_exp_f32_e32 v178, v178
	v_exp_f32_e32 v179, v179
	v_exp_f32_e32 v180, v180
	v_exp_f32_e32 v181, v181
	v_exp_f32_e32 v182, v182
	v_exp_f32_e32 v183, v183
	v_pk_add_f32 v[176:177], v[176:177], 1.0 op_sel_hi:[1,0]
	v_pk_add_f32 v[178:179], v[178:179], 1.0 op_sel_hi:[1,0]
	v_pk_add_f32 v[180:181], v[180:181], 1.0 op_sel_hi:[1,0]
	v_pk_add_f32 v[182:183], v[182:183], 1.0 op_sel_hi:[1,0]
	v_rcp_f32_e32 v176, v176
	v_rcp_f32_e32 v177, v177
	v_rcp_f32_e32 v178, v178
	v_rcp_f32_e32 v179, v179
	v_rcp_f32_e32 v180, v180
	v_rcp_f32_e32 v181, v181
	v_rcp_f32_e32 v182, v182
	v_rcp_f32_e32 v183, v183
	v_pk_mul_f32 v[176:177], v[126:127], v[176:177]
	v_pk_mul_f32 v[178:179], v[128:129], v[178:179]
	v_pk_mul_f32 v[180:181], v[122:123], v[180:181]
	v_pk_mul_f32 v[182:183], v[124:125], v[182:183]
	v_pk_mul_f32 v[176:177], v[176:177], v[118:119]
	v_pk_mul_f32 v[178:179], v[178:179], v[120:121]
	v_pk_mul_f32 v[180:181], v[180:181], v[114:115]
	v_pk_mul_f32 v[182:183], v[182:183], v[116:117]
	v_cvt_pk_bf16_f32 v184, v176, v177
	v_cvt_pk_bf16_f32 v185, v178, v179
	v_cvt_pk_bf16_f32 v186, v180, v181
	v_cvt_pk_bf16_f32 v187, v182, v183
	global_store_dwordx4 v[188:189], v[184:187], off
	v_or_b32_e32 v212, 16, v156
	v_mad_i64_i32 v[210:211], s[2:3], v212, s44, v[146:147]
	v_lshl_add_u64 v[210:211], v[210:211], 0, v[148:149]
	v_pk_mul_f32 v[198:199], v[110:111], s[98:99] op_sel_hi:[1,0]
	v_pk_mul_f32 v[200:201], v[112:113], s[98:99] op_sel_hi:[1,0]
	v_pk_mul_f32 v[202:203], v[106:107], s[98:99] op_sel_hi:[1,0]
	v_pk_mul_f32 v[204:205], v[108:109], s[98:99] op_sel_hi:[1,0]
	v_exp_f32_e32 v198, v198
	v_exp_f32_e32 v199, v199
	v_exp_f32_e32 v200, v200
	v_exp_f32_e32 v201, v201
	v_exp_f32_e32 v202, v202
	v_exp_f32_e32 v203, v203
	v_exp_f32_e32 v204, v204
	v_exp_f32_e32 v205, v205
	v_pk_add_f32 v[198:199], v[198:199], 1.0 op_sel_hi:[1,0]
	v_pk_add_f32 v[200:201], v[200:201], 1.0 op_sel_hi:[1,0]
	v_pk_add_f32 v[202:203], v[202:203], 1.0 op_sel_hi:[1,0]
	v_pk_add_f32 v[204:205], v[204:205], 1.0 op_sel_hi:[1,0]
	v_rcp_f32_e32 v198, v198
	v_rcp_f32_e32 v199, v199
	v_rcp_f32_e32 v200, v200
	v_rcp_f32_e32 v201, v201
	v_rcp_f32_e32 v202, v202
	v_rcp_f32_e32 v203, v203
	v_rcp_f32_e32 v204, v204
	v_rcp_f32_e32 v205, v205
	v_pk_mul_f32 v[198:199], v[110:111], v[198:199]
	v_pk_mul_f32 v[200:201], v[112:113], v[200:201]
	v_pk_mul_f32 v[202:203], v[106:107], v[202:203]
	v_pk_mul_f32 v[204:205], v[108:109], v[204:205]
	v_pk_mul_f32 v[198:199], v[198:199], v[102:103]
	v_pk_mul_f32 v[200:201], v[200:201], v[104:105]
	v_pk_mul_f32 v[202:203], v[202:203], v[98:99]
	v_pk_mul_f32 v[204:205], v[204:205], v[100:101]
	v_cvt_pk_bf16_f32 v206, v198, v199
	v_cvt_pk_bf16_f32 v207, v200, v201
	v_cvt_pk_bf16_f32 v208, v202, v203
	v_cvt_pk_bf16_f32 v209, v204, v205
	global_store_dwordx4 v[210:211], v[206:209], off
	v_or_b32_e32 v190, 32, v156
	v_mad_i64_i32 v[188:189], s[2:3], v190, s44, v[146:147]
	v_lshl_add_u64 v[188:189], v[188:189], 0, v[148:149]
	v_pk_mul_f32 v[176:177], v[94:95], s[98:99] op_sel_hi:[1,0]
	v_pk_mul_f32 v[178:179], v[96:97], s[98:99] op_sel_hi:[1,0]
	v_pk_mul_f32 v[180:181], v[90:91], s[98:99] op_sel_hi:[1,0]
	v_pk_mul_f32 v[182:183], v[92:93], s[98:99] op_sel_hi:[1,0]
	v_exp_f32_e32 v176, v176
	v_exp_f32_e32 v177, v177
	v_exp_f32_e32 v178, v178
	v_exp_f32_e32 v179, v179
	v_exp_f32_e32 v180, v180
	v_exp_f32_e32 v181, v181
	v_exp_f32_e32 v182, v182
	v_exp_f32_e32 v183, v183
	v_pk_add_f32 v[176:177], v[176:177], 1.0 op_sel_hi:[1,0]
	v_pk_add_f32 v[178:179], v[178:179], 1.0 op_sel_hi:[1,0]
	v_pk_add_f32 v[180:181], v[180:181], 1.0 op_sel_hi:[1,0]
	v_pk_add_f32 v[182:183], v[182:183], 1.0 op_sel_hi:[1,0]
	v_rcp_f32_e32 v176, v176
	v_rcp_f32_e32 v177, v177
	v_rcp_f32_e32 v178, v178
	v_rcp_f32_e32 v179, v179
	v_rcp_f32_e32 v180, v180
	v_rcp_f32_e32 v181, v181
	v_rcp_f32_e32 v182, v182
	v_rcp_f32_e32 v183, v183
	v_pk_mul_f32 v[176:177], v[94:95], v[176:177]
	v_pk_mul_f32 v[178:179], v[96:97], v[178:179]
	v_pk_mul_f32 v[180:181], v[90:91], v[180:181]
	v_pk_mul_f32 v[182:183], v[92:93], v[182:183]
	v_pk_mul_f32 v[176:177], v[176:177], v[86:87]
	v_pk_mul_f32 v[178:179], v[178:179], v[88:89]
	v_pk_mul_f32 v[180:181], v[180:181], v[82:83]
	v_pk_mul_f32 v[182:183], v[182:183], v[84:85]
	v_cvt_pk_bf16_f32 v184, v176, v177
	v_cvt_pk_bf16_f32 v185, v178, v179
	v_cvt_pk_bf16_f32 v186, v180, v181
	v_cvt_pk_bf16_f32 v187, v182, v183
	global_store_dwordx4 v[188:189], v[184:187], off
	v_or_b32_e32 v212, 48, v156
	v_mad_i64_i32 v[210:211], s[2:3], v212, s44, v[146:147]
	v_lshl_add_u64 v[210:211], v[210:211], 0, v[148:149]
	v_pk_mul_f32 v[198:199], v[78:79], s[98:99] op_sel_hi:[1,0]
	v_pk_mul_f32 v[200:201], v[80:81], s[98:99] op_sel_hi:[1,0]
	v_pk_mul_f32 v[202:203], v[74:75], s[98:99] op_sel_hi:[1,0]
	v_pk_mul_f32 v[204:205], v[76:77], s[98:99] op_sel_hi:[1,0]
	v_exp_f32_e32 v198, v198
	v_exp_f32_e32 v199, v199
	v_exp_f32_e32 v200, v200
	v_exp_f32_e32 v201, v201
	v_exp_f32_e32 v202, v202
	v_exp_f32_e32 v203, v203
	v_exp_f32_e32 v204, v204
	v_exp_f32_e32 v205, v205
; __device__ __forceinline__ unsigned cvt_pk_bf16(float lo, float hi) { unsigned r; asm volatile("v_cvt_pk_bf16_f32 %0, %1, %2" : "=v"(r) : "v"(lo), "v"(hi)); return r; }
; __device__ __forceinline__ float silu_f(float x) { return x * __builtin_amdgcn_rcpf(1.0f + __builtin_amdgcn_exp2f(-1.4426950408889634f * x)); }
;     __device__ __forceinline__ void operator()(const f32x4 (&acc)[2][2][4][2], const Unit& u, int wr, int wc, int fr, int fq) const {
;         const int row0 = u.pm * BM + wr * 64 + fr, col0 = u.pn * HALF + wc * 32 + 8 * fq;
; #pragma unroll
;         for (int ai = 0; ai < 2; ++ai)
; #pragma unroll
;             for (int m = 0; m < 4; ++m) { bf16_t* rowp = H + (size_t)(row0 + ai * HALF + m * 16) * ldc + col0;
;                 const f32x4 g0 = acc[ai][0][m][0], g1 = acc[ai][0][m][1], u0 = acc[ai][1][m][0], u1 = acc[ai][1][m][1];
;                 u32x4 w;
;                 w.x = cvt_pk_bf16(silu_f(g0[0]) * u0[0], silu_f(g0[1]) * u0[1]); w.y = cvt_pk_bf16(silu_f(g0[2]) * u0[2], silu_f(g0[3]) * u0[3]);
;                 w.z = cvt_pk_bf16(silu_f(g1[0]) * u1[0], silu_f(g1[1]) * u1[1]); w.w = cvt_pk_bf16(silu_f(g1[2]) * u1[2], silu_f(g1[3]) * u1[3]);
;                 *(u32x4*)rowp = w; }
	v_pk_add_f32 v[198:199], v[198:199], 1.0 op_sel_hi:[1,0]
	v_pk_add_f32 v[200:201], v[200:201], 1.0 op_sel_hi:[1,0]
	v_pk_add_f32 v[202:203], v[202:203], 1.0 op_sel_hi:[1,0]
	v_pk_add_f32 v[204:205], v[204:205], 1.0 op_sel_hi:[1,0]
	v_rcp_f32_e32 v198, v198
	v_rcp_f32_e32 v199, v199
	v_rcp_f32_e32 v200, v200
	v_rcp_f32_e32 v201, v201
	v_rcp_f32_e32 v202, v202
	v_rcp_f32_e32 v203, v203
	v_rcp_f32_e32 v204, v204
	v_rcp_f32_e32 v205, v205
	v_pk_mul_f32 v[198:199], v[78:79], v[198:199]
	v_pk_mul_f32 v[200:201], v[80:81], v[200:201]
	v_pk_mul_f32 v[202:203], v[74:75], v[202:203]
	v_pk_mul_f32 v[204:205], v[76:77], v[204:205]
	v_pk_mul_f32 v[198:199], v[198:199], v[70:71]
	v_pk_mul_f32 v[200:201], v[200:201], v[72:73]
	v_pk_mul_f32 v[202:203], v[202:203], v[66:67]
	v_pk_mul_f32 v[204:205], v[204:205], v[68:69]
	v_cvt_pk_bf16_f32 v206, v198, v199
	v_cvt_pk_bf16_f32 v207, v200, v201
	v_cvt_pk_bf16_f32 v208, v202, v203
	v_cvt_pk_bf16_f32 v209, v204, v205
	global_store_dwordx4 v[210:211], v[206:209], off
	v_add_u32_e32 v190, 0x80, v156
	v_mad_i64_i32 v[188:189], s[2:3], v190, s44, v[146:147]
	v_lshl_add_u64 v[188:189], v[188:189], 0, v[148:149]
	v_pk_mul_f32 v[176:177], v[62:63], s[98:99] op_sel_hi:[1,0]
	v_pk_mul_f32 v[178:179], v[64:65], s[98:99] op_sel_hi:[1,0]
	v_pk_mul_f32 v[180:181], v[58:59], s[98:99] op_sel_hi:[1,0]
	v_pk_mul_f32 v[182:183], v[60:61], s[98:99] op_sel_hi:[1,0]
	v_exp_f32_e32 v176, v176
	v_exp_f32_e32 v177, v177
	v_exp_f32_e32 v178, v178
	v_exp_f32_e32 v179, v179
	v_exp_f32_e32 v180, v180
	v_exp_f32_e32 v181, v181
	v_exp_f32_e32 v182, v182
	v_exp_f32_e32 v183, v183
	v_pk_add_f32 v[176:177], v[176:177], 1.0 op_sel_hi:[1,0]
	v_pk_add_f32 v[178:179], v[178:179], 1.0 op_sel_hi:[1,0]
	v_pk_add_f32 v[180:181], v[180:181], 1.0 op_sel_hi:[1,0]
	v_pk_add_f32 v[182:183], v[182:183], 1.0 op_sel_hi:[1,0]
	v_rcp_f32_e32 v176, v176
	v_rcp_f32_e32 v177, v177
	v_rcp_f32_e32 v178, v178
	v_rcp_f32_e32 v179, v179
	v_rcp_f32_e32 v180, v180
	v_rcp_f32_e32 v181, v181
	v_rcp_f32_e32 v182, v182
	v_rcp_f32_e32 v183, v183
	v_pk_mul_f32 v[176:177], v[62:63], v[176:177]
	v_pk_mul_f32 v[178:179], v[64:65], v[178:179]
	v_pk_mul_f32 v[180:181], v[58:59], v[180:181]
	v_pk_mul_f32 v[182:183], v[60:61], v[182:183]
	v_pk_mul_f32 v[176:177], v[176:177], v[54:55]
	v_pk_mul_f32 v[178:179], v[178:179], v[56:57]
	v_pk_mul_f32 v[180:181], v[180:181], v[50:51]
	v_pk_mul_f32 v[182:183], v[182:183], v[52:53]
	v_cvt_pk_bf16_f32 v184, v176, v177
	v_cvt_pk_bf16_f32 v185, v178, v179
	v_cvt_pk_bf16_f32 v186, v180, v181
	v_cvt_pk_bf16_f32 v187, v182, v183
	global_store_dwordx4 v[188:189], v[184:187], off
	v_add_u32_e32 v212, 0x90, v156
	v_mad_i64_i32 v[210:211], s[2:3], v212, s44, v[146:147]
	v_lshl_add_u64 v[210:211], v[210:211], 0, v[148:149]
	v_pk_mul_f32 v[198:199], v[46:47], s[98:99] op_sel_hi:[1,0]
	v_pk_mul_f32 v[200:201], v[48:49], s[98:99] op_sel_hi:[1,0]
	v_pk_mul_f32 v[202:203], v[42:43], s[98:99] op_sel_hi:[1,0]
	v_pk_mul_f32 v[204:205], v[44:45], s[98:99] op_sel_hi:[1,0]
	v_exp_f32_e32 v198, v198
	v_exp_f32_e32 v199, v199
	v_exp_f32_e32 v200, v200
	v_exp_f32_e32 v201, v201
	v_exp_f32_e32 v202, v202
	v_exp_f32_e32 v203, v203
	v_exp_f32_e32 v204, v204
	v_exp_f32_e32 v205, v205
	v_pk_add_f32 v[198:199], v[198:199], 1.0 op_sel_hi:[1,0]
	v_pk_add_f32 v[200:201], v[200:201], 1.0 op_sel_hi:[1,0]
	v_pk_add_f32 v[202:203], v[202:203], 1.0 op_sel_hi:[1,0]
	v_pk_add_f32 v[204:205], v[204:205], 1.0 op_sel_hi:[1,0]
	v_rcp_f32_e32 v198, v198
	v_rcp_f32_e32 v199, v199
	v_rcp_f32_e32 v200, v200
	v_rcp_f32_e32 v201, v201
	v_rcp_f32_e32 v202, v202
	v_rcp_f32_e32 v203, v203
	v_rcp_f32_e32 v204, v204
	v_rcp_f32_e32 v205, v205
	v_pk_mul_f32 v[198:199], v[46:47], v[198:199]
	v_pk_mul_f32 v[200:201], v[48:49], v[200:201]
	v_pk_mul_f32 v[202:203], v[42:43], v[202:203]
; __device__ __forceinline__ unsigned cvt_pk_bf16(float lo, float hi) { unsigned r; asm volatile("v_cvt_pk_bf16_f32 %0, %1, %2" : "=v"(r) : "v"(lo), "v"(hi)); return r; }
; __device__ __forceinline__ float silu_f(float x) { return x * __builtin_amdgcn_rcpf(1.0f + __builtin_amdgcn_exp2f(-1.4426950408889634f * x)); }
;     __device__ __forceinline__ void operator()(const f32x4 (&acc)[2][2][4][2], const Unit& u, int wr, int wc, int fr, int fq) const {
;         const int row0 = u.pm * BM + wr * 64 + fr, col0 = u.pn * HALF + wc * 32 + 8 * fq;
; #pragma unroll
;         for (int ai = 0; ai < 2; ++ai)
; #pragma unroll
;             for (int m = 0; m < 4; ++m) { bf16_t* rowp = H + (size_t)(row0 + ai * HALF + m * 16) * ldc + col0;
;                 const f32x4 g0 = acc[ai][0][m][0], g1 = acc[ai][0][m][1], u0 = acc[ai][1][m][0], u1 = acc[ai][1][m][1];
;                 u32x4 w;
;                 w.x = cvt_pk_bf16(silu_f(g0[0]) * u0[0], silu_f(g0[1]) * u0[1]); w.y = cvt_pk_bf16(silu_f(g0[2]) * u0[2], silu_f(g0[3]) * u0[3]);
;                 w.z = cvt_pk_bf16(silu_f(g1[0]) * u1[0], silu_f(g1[1]) * u1[1]); w.w = cvt_pk_bf16(silu_f(g1[2]) * u1[2], silu_f(g1[3]) * u1[3]);
;                 *(u32x4*)rowp = w; }
; template <class Epi, class Sched, bool ALIGN_EPI = false, bool SP2 = false>
; __device__ __forceinline__ void gemm_phase(PG8_LAS unsigned char* lds, const Gemm g, const Sched& S, const Epi& E) {
;     ...
;         if constexpr (!Epi::AFTER_DRAIN) { E(acc, cur, wr, wc, fr, fq); S.done(cur); }
;         if (!has_next) break;
	v_pk_mul_f32 v[204:205], v[44:45], v[204:205]
	v_pk_mul_f32 v[198:199], v[198:199], v[38:39]
	v_pk_mul_f32 v[200:201], v[200:201], v[40:41]
	v_pk_mul_f32 v[202:203], v[202:203], v[34:35]
	v_pk_mul_f32 v[204:205], v[204:205], v[36:37]
	v_cvt_pk_bf16_f32 v206, v198, v199
	v_cvt_pk_bf16_f32 v207, v200, v201
	v_cvt_pk_bf16_f32 v208, v202, v203
	v_cvt_pk_bf16_f32 v209, v204, v205
	global_store_dwordx4 v[210:211], v[206:209], off
	v_add_u32_e32 v190, 0xa0, v156
	v_mad_i64_i32 v[188:189], s[2:3], v190, s44, v[146:147]
	v_lshl_add_u64 v[188:189], v[188:189], 0, v[148:149]
	v_pk_mul_f32 v[176:177], v[30:31], s[98:99] op_sel_hi:[1,0]
	v_pk_mul_f32 v[178:179], v[32:33], s[98:99] op_sel_hi:[1,0]
	v_pk_mul_f32 v[180:181], v[26:27], s[98:99] op_sel_hi:[1,0]
	v_pk_mul_f32 v[182:183], v[28:29], s[98:99] op_sel_hi:[1,0]
	v_exp_f32_e32 v176, v176
	v_exp_f32_e32 v177, v177
	v_exp_f32_e32 v178, v178
	v_exp_f32_e32 v179, v179
	v_exp_f32_e32 v180, v180
	v_exp_f32_e32 v181, v181
	v_exp_f32_e32 v182, v182
	v_exp_f32_e32 v183, v183
	v_pk_add_f32 v[176:177], v[176:177], 1.0 op_sel_hi:[1,0]
	v_pk_add_f32 v[178:179], v[178:179], 1.0 op_sel_hi:[1,0]
	v_pk_add_f32 v[180:181], v[180:181], 1.0 op_sel_hi:[1,0]
	v_pk_add_f32 v[182:183], v[182:183], 1.0 op_sel_hi:[1,0]
	v_rcp_f32_e32 v176, v176
	v_rcp_f32_e32 v177, v177
	v_rcp_f32_e32 v178, v178
	v_rcp_f32_e32 v179, v179
	v_rcp_f32_e32 v180, v180
	v_rcp_f32_e32 v181, v181
	v_rcp_f32_e32 v182, v182
	v_rcp_f32_e32 v183, v183
	v_pk_mul_f32 v[176:177], v[30:31], v[176:177]
	v_pk_mul_f32 v[178:179], v[32:33], v[178:179]
	v_pk_mul_f32 v[180:181], v[26:27], v[180:181]
	v_pk_mul_f32 v[182:183], v[28:29], v[182:183]
	v_pk_mul_f32 v[176:177], v[176:177], v[22:23]
	v_pk_mul_f32 v[178:179], v[178:179], v[24:25]
	v_pk_mul_f32 v[180:181], v[180:181], v[18:19]
	v_pk_mul_f32 v[182:183], v[182:183], v[20:21]
	v_cvt_pk_bf16_f32 v184, v176, v177
	v_cvt_pk_bf16_f32 v185, v178, v179
	v_cvt_pk_bf16_f32 v186, v180, v181
	v_cvt_pk_bf16_f32 v187, v182, v183
	global_store_dwordx4 v[188:189], v[184:187], off
	v_add_u32_e32 v212, 0xb0, v156
	v_mad_i64_i32 v[210:211], s[2:3], v212, s44, v[146:147]
	v_lshl_add_u64 v[210:211], v[210:211], 0, v[148:149]
	v_pk_mul_f32 v[198:199], v[14:15], s[98:99] op_sel_hi:[1,0]
	v_pk_mul_f32 v[200:201], v[16:17], s[98:99] op_sel_hi:[1,0]
	v_pk_mul_f32 v[202:203], v[10:11], s[98:99] op_sel_hi:[1,0]
	v_pk_mul_f32 v[204:205], v[12:13], s[98:99] op_sel_hi:[1,0]
	v_exp_f32_e32 v198, v198
	v_exp_f32_e32 v199, v199
	v_exp_f32_e32 v200, v200
	v_exp_f32_e32 v201, v201
	v_exp_f32_e32 v202, v202
	v_exp_f32_e32 v203, v203
	v_exp_f32_e32 v204, v204
	v_exp_f32_e32 v205, v205
	v_pk_add_f32 v[198:199], v[198:199], 1.0 op_sel_hi:[1,0]
	v_pk_add_f32 v[200:201], v[200:201], 1.0 op_sel_hi:[1,0]
	v_pk_add_f32 v[202:203], v[202:203], 1.0 op_sel_hi:[1,0]
	v_pk_add_f32 v[204:205], v[204:205], 1.0 op_sel_hi:[1,0]
	v_rcp_f32_e32 v198, v198
	v_rcp_f32_e32 v199, v199
	v_rcp_f32_e32 v200, v200
	v_rcp_f32_e32 v201, v201
	v_rcp_f32_e32 v202, v202
	v_rcp_f32_e32 v203, v203
	v_rcp_f32_e32 v204, v204
	v_rcp_f32_e32 v205, v205
	v_pk_mul_f32 v[198:199], v[14:15], v[198:199]
	v_pk_mul_f32 v[200:201], v[16:17], v[200:201]
	v_pk_mul_f32 v[202:203], v[10:11], v[202:203]
	v_pk_mul_f32 v[204:205], v[12:13], v[204:205]
	v_pk_mul_f32 v[198:199], v[198:199], v[6:7]
	v_pk_mul_f32 v[200:201], v[200:201], v[8:9]
	v_pk_mul_f32 v[202:203], v[202:203], v[2:3]
	v_pk_mul_f32 v[204:205], v[204:205], v[4:5]
	v_cvt_pk_bf16_f32 v206, v198, v199
	v_cvt_pk_bf16_f32 v207, v200, v201
	v_cvt_pk_bf16_f32 v208, v202, v203
	v_cvt_pk_bf16_f32 v209, v204, v205
	global_store_dwordx4 v[210:211], v[206:209], off
	s_andn2_b64 vcc, exec, s[6:7]
	s_mov_b64 s[2:3], -1
	s_cbranch_vccnz .LBB0_1620
	s_andn2_b64 vcc, exec, s[0:1]
	s_cbranch_vccnz .LBB0_1619
	s_barrier
	s_branch .LBB0_1619
